# slot fusion v2 + phase-4 item order reversed per CU mate (blockIdx bit 8) instead of per XCD
# speedup vs baseline: 1.0076x; 1.0076x over previous
; DEVI int ltid() { int t = threadIdx.x; asm volatile("" : "+v"(t)); return t; }
; DEVI void h3_item(const Params& P, int l, int ck, int h, char* smem, int tid) {
;   const ChunkInfo ci = chunkinfo(ck);
;   const int lane = tid & 63, w = tid >> 6, fr = lane & 15, fq = lane >> 4;
;   bfu* QT = (bfu*)smem;
;   bfu* KT = QT + 64 * 136;
;   bfu* AT = KT + 64 * 136;
;   bfu* BS = AT + 64 * 72;
;   float* bmid = (float*)(BS + 128 * 72);
;   const int d = tid & 127, hf = tid >> 7, L = ci.L, Lh = L >> 1;
;   const float lb = ((const float*)(P.ws + O_LBS))[l * 1024 + h * 128 + d];
;   const bfu* Z = (const bfu*)(P.ws + O_Z);
;   const bfu* zqb = Z + (long)ci.lt0 * NCOL + 5 * 1024 + h * 128;
;   __syncthreads();
;   {
;     uint4 vq[4], vf[4], vi[4];
; #pragma unroll
;     for (int q = 0; q < 4; ++q) {
;       const int idx = tid + 256 * q;
;       const int sr = (idx & 15) | (((idx >> 8) & 3) << 4), c16 = ((idx >> 4) & 3) | (((idx >> 6) & 3) << 2);
; DEVI void phase4(const Params& P, int l, int pass, char* smem) {
;   const int tid = ltid();
;   const int ntok = pass ? 8192 : 8448;
;   const int nck = pass ? 128 : 136;
;   const int nH = nck * 8;
;   const int nA = (ntok / 128) * 4;
;   const int nM = ntok / 128, nT = nM * 8;
;   for (int id = blockIdx.x; id < nA + nH + nT; id += gridDim.x) {
;     if (id < nA) apply_item(P, l, pass, id, tid);
;     else if (id < nA + nH) { int q = id - nA; h3_item(P, l, q >> 3, q & 7, smem, tid); }
;     else { int pm, pn; tile_rc_m(id - nA - nH, nM, 8, pm, pn); p6_branch<0, 0, 0>(P, pm, pn, nullptr, smem, tid); }
;   }
.LBB0_501:
	s_mov_b32 s91, 0x20000
	s_or_b64 exec, exec, s[26:27]
	s_barrier
	s_cmp_eq_u32 s90, 0
	s_cselect_b64 s[26:27], -1, 0
	s_and_b64 s[40:41], s[26:27], exec
	s_movk_i32 s1, 0x440
	s_cselect_b32 s24, 0x42, 64
	s_cselect_b32 s2, s1, 0x400
	s_lshl_b32 s1, s24, 2
	s_lshl_b32 s24, s24, 3
	s_or_b32 s60, s1, s2
	s_or_b32 s44, s60, s24
	v_mov_b32_e32 v91, v93
	s_cmp_ge_i32 s74, s44
	s_cbranch_scc1 .LBB0_691
	v_lshlrev_b32_e32 v101, 4, v91
	v_add_u32_e32 v107, 0x3000, v101
	v_ashrrev_i32_e32 v18, 7, v107
	v_xor_b32_e32 v17, v18, v91
	v_lshlrev_b32_e32 v17, 3, v17
	v_and_b32_e32 v22, 56, v17
	v_and_b32_e32 v17, 15, v91
	v_lshrrev_b32_e32 v23, 1, v91
	s_mov_b32 s2, 0x1ffffc0
	v_and_or_b32 v24, v23, s2, v17
	v_lshrrev_b32_e32 v3, 4, v91
	v_bfe_u32 v7, v91, 4, 2
	v_and_b32_e32 v25, 7, v91
	v_lshlrev_b32_e32 v164, 7, v24
	v_lshlrev_b32_e32 v24, 7, v91
	v_bitop3_b32 v26, v3, v25, 3 bitop3:0x6c
	v_and_b32_e32 v165, 0x2780, v24
	v_bitop3_b32 v24, v7, v25, 4 bitop3:0x36
	v_lshrrev_b32_e32 v25, 2, v91
	v_and_b32_e32 v25, 12, v25
	s_mov_b32 s2, 0x7fffc0
	v_lshlrev_b32_e32 v166, 4, v24
	v_and_b32_e32 v24, 64, v91
	v_and_or_b32 v25, v23, s2, v25
	v_and_b32_e32 v3, 48, v3
	v_lshlrev_b32_e32 v109, 4, v26
	v_lshlrev_b32_e32 v26, 2, v24
	v_lshlrev_b32_e32 v24, 2, v17
	v_lshlrev_b32_e32 v25, 9, v25
	v_and_b32_e32 v100, 0x78, v23
	v_or_b32_e32 v171, v3, v17
	v_add_u32_e32 v23, 0x100, v91
	v_bitop3_b32 v173, v3, 32, v17 bitop3:0x36
	v_add_u32_e32 v3, 0x300, v91
	v_or3_b32 v167, v26, v24, v25
	v_lshlrev_b32_e32 v25, 2, v91
	v_lshrrev_b32_e32 v23, 4, v23
	v_lshrrev_b32_e32 v3, 4, v3
	v_and_b32_e32 v168, 0x7c, v25
	v_and_or_b32 v172, v23, 48, v17
	v_and_or_b32 v174, v3, 48, v17
	v_lshlrev_b32_e32 v3, 1, v100
	v_mul_u32_u24_e32 v23, 0x88, v171
	v_mul_u32_u24_e32 v25, 0x48, v100
	s_movk_i32 s2, 0x8e
	v_lshl_add_u32 v175, v23, 1, v3
	v_lshlrev_b32_e32 v23, 1, v171
	v_lshlrev_b32_e32 v25, 1, v25
	v_mad_u32_u24 v26, v100, s2, v3
	v_or_b32_e32 v176, v23, v25
	v_add_u32_e32 v177, v26, v23
	v_mul_u32_u24_e32 v23, 0x88, v172
	v_lshl_add_u32 v178, v23, 1, v3
	v_lshlrev_b32_e32 v23, 1, v172
	v_or_b32_e32 v179, v23, v25
	v_add_u32_e32 v180, v26, v23
	v_mul_u32_u24_e32 v23, 0x88, v173
	v_lshl_add_u32 v181, v23, 1, v3
	v_lshlrev_b32_e32 v23, 1, v173
	v_or_b32_e32 v182, v23, v25
	v_add_u32_e32 v183, v26, v23
	v_mul_u32_u24_e32 v23, 0x88, v174
	s_movk_i32 s2, 0x7f
	v_ashrrev_i32_e32 v31, 7, v91
	v_lshl_add_u32 v196, v23, 1, v3
	v_lshlrev_b32_e32 v23, 1, v174
	v_cmp_lt_u32_e64 s[4:5], s2, v91
	s_movk_i32 s2, 0x880
	v_and_b32_e32 v27, 0x7f, v91
	v_or_b32_e32 v197, v23, v25
	v_add_u32_e32 v198, v26, v23
	v_mul_lo_u32 v23, v31, s2
	v_or_b32_e32 v23, v23, v27
	v_lshlrev_b32_e32 v200, 1, v23
	v_ashrrev_i32_e32 v23, 2, v91
	v_and_b32_e32 v25, -16, v23
	v_writelane_b32 v252, s4, 37
	v_lshl_or_b32 v201, v7, 2, v25
	v_or_b32_e32 v202, 1, v201
	v_writelane_b32 v252, s5, 38
	v_cmp_gt_i32_e64 s[4:5], v17, v201
	v_cmp_gt_i32_e64 s[6:7], v17, v202
	v_or_b32_e32 v203, 2, v201
	v_writelane_b32 v252, s4, 34
	v_or_b32_e32 v204, 3, v201
	v_or_b32_e32 v29, 16, v17
	v_writelane_b32 v252, s5, 35
	v_writelane_b32 v252, s6, 39
	v_or_b32_e32 v30, 32, v17
	v_cmp_gt_i32_e64 s[64:65], v30, v204
	v_writelane_b32 v252, s7, 40
	v_cmp_gt_i32_e64 s[6:7], v17, v203
	s_lshl_b32 s50, s0, 7
	v_bfi_b32 v23, -16, v23, v91
	v_writelane_b32 v252, s6, 41
	v_lshlrev_b32_e32 v26, 4, v7
	v_or_b32_e32 v32, 48, v17
	v_writelane_b32 v252, s7, 42
	v_cmp_gt_i32_e64 s[6:7], v17, v204
	s_movk_i32 s4, 0x90
	s_lshl_b32 s45, s0, 6
	v_writelane_b32 v252, s6, 43
	v_ashrrev_i32_e32 v25, 1, v91
	s_ashr_i32 s51, s50, 31
	v_writelane_b32 v252, s7, 44
	v_cmp_gt_i32_e64 s[6:7], v29, v201
	v_cmp_gt_i32_e64 s[66:67], v32, v201
	v_cmp_gt_i32_e64 s[40:41], v32, v202
	v_writelane_b32 v252, s6, 45
	v_cmp_gt_i32_e64 s[42:43], v32, v203
	v_cmp_gt_i32_e64 s[62:63], v32, v204
	v_writelane_b32 v252, s7, 46
	v_cmp_gt_i32_e64 s[6:7], v29, v202
	v_mad_u64_u32 v[110:111], s[46:47], v23, s4, v[26:27]
	s_nop 0
	v_writelane_b32 v252, s6, 47
	v_lshlrev_b32_e32 v32, 7, v25
	s_and_b64 s[26:27], s[26:27], exec
	v_writelane_b32 v252, s7, 48
	v_cmp_gt_i32_e64 s[6:7], v29, v203
	v_readlane_b32 s52, v253, 6
	v_mul_lo_u32 v7, v201, s4
	v_writelane_b32 v252, s6, 49
	v_ashrrev_i32_e32 v33, 31, v32
	v_readlane_b32 s58, v253, 12
	v_writelane_b32 v252, s7, 50
	v_cmp_gt_i32_e64 s[6:7], v29, v204
; DEVI int ltid() { int t = threadIdx.x; asm volatile("" : "+v"(t)); return t; }
; DEVI void h3_item(const Params& P, int l, int ck, int h, char* smem, int tid) {
;   const ChunkInfo ci = chunkinfo(ck);
;   const int lane = tid & 63, w = tid >> 6, fr = lane & 15, fq = lane >> 4;
;   bfu* QT = (bfu*)smem;
;   bfu* KT = QT + 64 * 136;
;   bfu* AT = KT + 64 * 136;
;   bfu* BS = AT + 64 * 72;
;   float* bmid = (float*)(BS + 128 * 72);
;   const int d = tid & 127, hf = tid >> 7, L = ci.L, Lh = L >> 1;
;   const float lb = ((const float*)(P.ws + O_LBS))[l * 1024 + h * 128 + d];
;   const bfu* Z = (const bfu*)(P.ws + O_Z);
;   const bfu* zqb = Z + (long)ci.lt0 * NCOL + 5 * 1024 + h * 128;
;   __syncthreads();
;   {
;     uint4 vq[4], vf[4], vi[4];
; #pragma unroll
;     for (int q = 0; q < 4; ++q) {
;       const int idx = tid + 256 * q;
;       const int sr = (idx & 15) | (((idx >> 8) & 3) << 4), c16 = ((idx >> 4) & 3) | (((idx >> 6) & 3) << 2);
; DEVI void phase4(const Params& P, int l, int pass, char* smem) {
;   const int tid = ltid();
;   const int ntok = pass ? 8192 : 8448;
;   const int nck = pass ? 128 : 136;
;   const int nH = nck * 8;
;   const int nA = (ntok / 128) * 4;
;   const int nM = ntok / 128, nT = nM * 8;
;   for (int id = blockIdx.x; id < nA + nH + nT; id += gridDim.x) {
;     if (id < nA) apply_item(P, l, pass, id, tid);
;     else if (id < nA + nH) { int q = id - nA; h3_item(P, l, q >> 3, q & 7, smem, tid); }
;     else { int pm, pn; tile_rc_m(id - nA - nH, nM, 8, pm, pn); p6_branch<0, 0, 0>(P, pm, pn, nullptr, smem, tid); }
;   }
	v_lshlrev_b32_e32 v29, 5, v91
	v_ashrrev_i32_e32 v8, 3, v91
	v_writelane_b32 v252, s6, 51
	v_add_u32_e32 v103, 0x1000, v101
	v_lshlrev_b64 v[32:33], 1, v[32:33]
	v_writelane_b32 v252, s7, 52
	v_cmp_gt_i32_e64 s[6:7], v30, v201
	v_readlane_b32 s59, v253, 13
	v_ashrrev_i32_e32 v9, 31, v8
	v_writelane_b32 v252, s6, 53
	v_ashrrev_i32_e32 v10, 7, v103
	v_xor_b32_e32 v2, v8, v91
	v_writelane_b32 v252, s7, 54
	v_cmp_gt_i32_e64 s[6:7], v30, v202
	v_lshlrev_b64 v[0:1], 10, v[8:9]
	v_ashrrev_i32_e32 v11, 31, v10
	v_writelane_b32 v252, s6, 55
	v_add_u32_e32 v105, 0x2000, v101
	v_lshlrev_b32_e32 v28, 1, v17
	v_writelane_b32 v252, s7, 56
	v_cmp_gt_i32_e64 s[6:7], v30, v203
	v_and_b32_e32 v30, 32, v29
	v_lshlrev_b32_e32 v88, 1, v30
	v_writelane_b32 v252, s6, 57
	v_mad_u64_u32 v[112:113], s[46:47], v25, s4, v[88:89]
	s_nop 0
	v_writelane_b32 v252, s7, 58
	s_cselect_b32 s46, 0, 0x2100
	s_lshl_b32 s47, s0, 3
	s_lshl_b32 s48, s0, 2
	v_readlane_b32 s4, v252, 10
	s_lshl_b64 s[26:27], s[50:51], 2
	v_readlane_b32 s5, v252, 11
	s_add_u32 s26, s58, s26
	s_addc_u32 s27, s59, s27
	v_lshl_add_u64 v[34:35], s[4:5], 0, v[32:33]
	v_mov_b32_e32 v25, v89
	v_readlane_b32 s4, v252, 12
	v_lshl_add_u64 v[118:119], s[26:27], 0, v[24:25]
	v_mov_b32_e32 v29, v89
	v_readlane_b32 s5, v252, 13
	v_lshlrev_b64 v[24:25], 11, v[8:9]
	v_bitop3_b32 v8, v8, 7, v91 bitop3:0x48
	v_xor_b32_e32 v6, v10, v91
	v_lshlrev_b64 v[4:5], 10, v[10:11]
	v_ashrrev_i32_e32 v12, 7, v105
	v_lshl_add_u64 v[120:121], s[4:5], 0, v[28:29]
	v_lshl_or_b32 v24, v8, 4, v24
	v_readlane_b32 s4, v252, 25
	v_lshlrev_b64 v[8:9], 11, v[10:11]
	v_bitop3_b32 v10, v10, 7, v91 bitop3:0x48
	v_ashrrev_i32_e32 v13, 31, v12
	v_readlane_b32 s5, v252, 26
	v_lshl_or_b32 v8, v10, 4, v8
	v_bitop3_b32 v10, v12, 7, v91 bitop3:0x48
	v_lshl_add_u64 v[124:125], s[4:5], 0, v[8:9]
	v_lshlrev_b64 v[8:9], 11, v[12:13]
	v_ashrrev_i32_e32 v19, 31, v18
	v_lshl_or_b32 v8, v10, 4, v8
	v_lshl_add_u64 v[126:127], s[4:5], 0, v[8:9]
	v_lshlrev_b64 v[8:9], 11, v[18:19]
	v_bitop3_b32 v10, v18, 7, v91 bitop3:0x48
	v_xor_b32_e32 v16, v12, v91
	s_movk_i32 s2, 0x110
	v_lshl_or_b32 v8, v10, 4, v8
	v_lshlrev_b32_e32 v2, 3, v2
	v_lshlrev_b32_e32 v6, 3, v6
	v_lshlrev_b32_e32 v16, 3, v16
	v_mul_lo_u32 v36, v23, s2
	v_mul_u32_u24_e32 v23, 0x90, v27
	v_mul_lo_u32 v42, v201, s2
	v_lshl_add_u64 v[128:129], s[4:5], 0, v[8:9]
	v_lshlrev_b32_e32 v8, 6, v31
	s_mov_b32 s2, 0xac00
	v_and_b32_e32 v2, 56, v2
	v_and_b32_e32 v6, 56, v6
	v_lshlrev_b64 v[14:15], 10, v[12:13]
	v_and_b32_e32 v16, 56, v16
	v_lshlrev_b64 v[20:21], 10, v[18:19]
	v_mul_u32_u24_e32 v37, 0x110, v17
	v_mul_u32_u24_e32 v38, 0x110, v171
	v_mul_u32_u24_e32 v39, 0x110, v172
	v_mul_u32_u24_e32 v40, 0x110, v173
	v_mul_u32_u24_e32 v41, 0x110, v174
	v_mul_u32_u24_e32 v17, 0x90, v17
	v_lshlrev_b32_e32 v113, 1, v27
	v_add3_u32 v206, v23, v8, s2
	v_and_b32_e32 v8, 0xffffff80, v91
	v_lshlrev_b32_e32 v169, 2, v168
	v_lshl_or_b32 v170, s0, 10, v27
	v_mul_u32_u24_e32 v102, 0x3000, v171
	v_mul_u32_u24_e32 v104, 0x3000, v172
	v_mul_u32_u24_e32 v106, 0x3000, v173
	v_mul_u32_u24_e32 v108, 0x3000, v174
	v_lshlrev_b32_e32 v199, 2, v27
	v_lshlrev_b32_e32 v111, 2, v30
	s_movk_i32 s37, 0x110
	v_lshl_add_u64 v[114:115], v[34:35], 0, v[88:89]
	v_lshl_add_u64 v[116:117], s[30:31], 0, v[32:33]
	v_lshl_add_u64 v[122:123], s[4:5], 0, v[24:25]
	v_add_u32_e32 v205, 0xfffff780, v113
	v_add_u32_e32 v207, 0xf400, v8
	v_lshl_or_b32 v208, v31, 12, v27
	v_add_u32_e32 v209, 0xf500, v8
	v_lshlrev_b64 v[130:131], 1, v[0:1]
	v_lshlrev_b32_e32 v132, 1, v2
	v_lshlrev_b64 v[134:135], 1, v[4:5]
	v_lshlrev_b32_e32 v136, 1, v6
	v_lshlrev_b64 v[138:139], 1, v[14:15]
	v_lshlrev_b32_e32 v140, 1, v16
	v_lshlrev_b64 v[142:143], 1, v[20:21]
	v_lshlrev_b32_e32 v144, 1, v22
	v_add_u32_e32 v210, v36, v26
	v_add_u32_e32 v211, v26, v37
	v_add_u32_e32 v212, v28, v7
	v_add_u32_e32 v213, v3, v38
	v_add_u32_e32 v214, v3, v39
	v_add_u32_e32 v215, v3, v40
	v_add_u32_e32 v216, v3, v41
	v_add_u32_e32 v217, v26, v17
	v_lshlrev_b32_e32 v146, 1, v30
	v_add_u32_e32 v218, v28, v42
	v_readlane_b32 s49, v252, 16
	s_mov_b32 s2, s74
	v_readlane_b32 s53, v253, 7
	v_readlane_b32 s54, v253, 8
	v_readlane_b32 s55, v253, 9
	v_readlane_b32 s56, v253, 10
	v_readlane_b32 s57, v253, 11
	v_readlane_b32 vcc_lo, v252, 32
	s_nop 1
	s_bitcmp1_b32 vcc_lo, 8
	s_cbranch_scc0 .LBB0_504

; DEVI void phase4(const Params& P, int l, int pass, char* smem) {
;     ...
;   for (int id = blockIdx.x; id < nA + nH + nT; id += gridDim.x) {
;     if (id < nA) apply_item(P, l, pass, id, tid);
;     else if (id < nA + nH) { int q = id - nA; h3_item(P, l, q >> 3, q & 7, smem, tid); }
;     else { int pm, pn; tile_rc_m(id - nA - nH, nM, 8, pm, pn); p6_branch<0, 0, 0>(P, pm, pn, nullptr, smem, tid); }
;   }
.LBB0_503:
	v_readlane_b32 s4, v252, 17
	v_readlane_b32 vcc_lo, v252, 32
	s_nop 1
	s_bitcmp1_b32 vcc_lo, 8
	s_cbranch_scc1 .Lp4_back
	s_add_i32 s2, s2, s23
	s_add_i32 s49, s49, s4
	s_cmp_lt_i32 s2, s44
	s_cbranch_scc0 .LBB0_690
	s_branch .LBB0_504
